# POOLMIX residual-stage old-residual loads nt (their last use)
# speedup vs baseline: 1.0109x; 1.0109x over previous
.LBB0_549:
	s_or_b64 exec, exec, s[26:27]
	v_add_u32_e32 v0, 0, v241
	v_add_u32_e32 v14, 0x20400, v0
	s_waitcnt lgkmcnt(0)
	s_barrier
	ds_read_b128 v[2:5], v14
	ds_read_b128 v[6:9], v14 offset:16
	v_or_b32_e32 v104, s63, v209
	v_ashrrev_i32_e32 v105, 31, v104
	v_mov_b32_e32 v106, 0
	s_waitcnt lgkmcnt(1)
	v_mov_b32_e32 v10, v3
	v_mov_b32_e32 v11, v4
	v_mov_b32_e32 v3, v5
	v_pk_add_f32 v[2:3], v[10:11], v[2:3]
	s_waitcnt lgkmcnt(0)
	v_mov_b32_e32 v4, v8
	v_mov_b32_e32 v5, v6
	v_mov_b32_e32 v6, v9
	v_pk_add_f32 v[4:5], v[4:5], v[6:7]
	v_add_f32_e32 v0, v2, v3
	v_add_f32_e32 v0, v0, v5
	v_add_f32_e32 v0, v4, v0
	v_fmamk_f32 v0, v0, 0x3a800000, v229
	v_cmp_gt_f32_e32 vcc, s5, v0
	v_mul_f32_e32 v2, 0x4f800000, v0
	s_nop 0
	v_cndmask_b32_e32 v0, v0, v2, vcc
	v_sqrt_f32_e32 v2, v0
	s_nop 0
	v_add_u32_e32 v3, -1, v2
	v_fma_f32 v4, -v3, v2, v0
	v_cmp_ge_f32_e64 s[42:43], 0, v4
	v_add_u32_e32 v4, 1, v2
	s_nop 0
	v_cndmask_b32_e64 v3, v2, v3, s[42:43]
	v_fma_f32 v2, -v4, v2, v0
	v_cmp_lt_f32_e64 s[42:43], 0, v2
	s_nop 1
	v_cndmask_b32_e64 v2, v3, v4, s[42:43]
	v_mul_f32_e32 v3, 0x37800000, v2
	v_cndmask_b32_e32 v2, v2, v3, vcc
	v_cmp_class_f32_e32 vcc, v0, v230
	s_nop 1
	v_cndmask_b32_e32 v0, v2, v0, vcc
	v_div_scale_f32 v2, s[16:17], v0, v0, 1.0
	v_rcp_f32_e32 v3, v2
	s_nop 0
	v_fma_f32 v4, -v2, v3, 1.0
	v_fmac_f32_e32 v3, v4, v3
	v_div_scale_f32 v4, vcc, 1.0, v0, 1.0
	v_mul_f32_e32 v5, v4, v3
	v_fma_f32 v6, -v2, v5, v4
	v_fmac_f32_e32 v5, v6, v3
	v_fma_f32 v2, -v2, v5, v4
	v_div_fmas_f32 v2, v2, v3, v5
	v_div_fixup_f32 v54, v2, v0, 1.0
	ds_read_b128 v[2:5], v14 offset:512
	ds_read_b128 v[6:9], v14 offset:528
	v_pk_mul_f32 v[68:69], v[176:177], v[54:55] op_sel_hi:[1,0]
	v_pk_mul_f32 v[112:113], v[174:175], v[54:55] op_sel_hi:[1,0]
	v_pk_mul_f32 v[114:115], v[172:173], v[54:55] op_sel_hi:[1,0]
	s_waitcnt lgkmcnt(1)
	v_add_f32_e32 v0, v2, v3
	v_add_f32_e32 v2, v4, v5
	v_add_f32_e32 v0, v0, v2
	s_waitcnt lgkmcnt(0)
	v_add_f32_e32 v2, v6, v7
	v_add_f32_e32 v0, v0, v2
	v_add_f32_e32 v2, v8, v9
	v_add_f32_e32 v0, v2, v0
	v_fmamk_f32 v0, v0, 0x3a800000, v229
	v_cmp_gt_f32_e32 vcc, s5, v0
	v_mul_f32_e32 v2, 0x4f800000, v0
	v_pk_mul_f32 v[116:117], v[170:171], v[54:55] op_sel_hi:[1,0]
	v_cndmask_b32_e32 v0, v0, v2, vcc
	v_sqrt_f32_e32 v2, v0
	s_nop 0
	v_add_u32_e32 v3, -1, v2
	v_fma_f32 v4, -v3, v2, v0
	v_cmp_ge_f32_e64 s[42:43], 0, v4
	v_add_u32_e32 v4, 1, v2
	s_nop 0
	v_cndmask_b32_e64 v3, v2, v3, s[42:43]
	v_fma_f32 v2, -v4, v2, v0
	v_cmp_lt_f32_e64 s[42:43], 0, v2
	s_nop 1
	v_cndmask_b32_e64 v2, v3, v4, s[42:43]
	v_mul_f32_e32 v3, 0x37800000, v2
	v_cndmask_b32_e32 v2, v2, v3, vcc
	v_cmp_class_f32_e32 vcc, v0, v230
	s_nop 1
	v_cndmask_b32_e32 v0, v2, v0, vcc
	v_div_scale_f32 v2, s[16:17], v0, v0, 1.0
	v_rcp_f32_e32 v3, v2
	s_nop 0
	v_fma_f32 v4, -v2, v3, 1.0
	v_fmac_f32_e32 v3, v4, v3
	v_div_scale_f32 v4, vcc, 1.0, v0, 1.0
	v_mul_f32_e32 v5, v4, v3
	v_fma_f32 v6, -v2, v5, v4
	v_fmac_f32_e32 v5, v6, v3
	v_fma_f32 v2, -v2, v5, v4
	v_div_fmas_f32 v2, v2, v3, v5
	v_div_fixup_f32 v0, v2, v0, 1.0
	v_lshlrev_b64 v[2:3], 10, v[104:105]
	v_lshl_add_u64 v[2:3], v[2:3], 0, v[212:213]
	v_lshlrev_b64 v[66:67], 1, v[2:3]
	v_lshl_add_u64 v[64:65], s[36:37], 0, v[66:67]
	ds_read_b128 v[26:29], v14 offset:1024
	ds_read_b128 v[22:25], v14 offset:1040
	ds_read_b128 v[10:13], v14 offset:1536
	ds_read_b128 v[6:9], v14 offset:1552
	global_load_dwordx4 v[14:17], v[218:219], off offset:16
	global_load_dwordx4 v[18:21], v[218:219], off
	global_load_dwordx4 v[2:5], v[64:65], off nt
	s_cmp_lg_u32 s68, 4
	s_cbranch_scc1 .Lpmh_skip0
	s_mov_b64 s[52:53], 0x8000
	s_mov_b64 s[54:55], 0x10000
	s_mov_b64 s[56:57], 0x18000
	v_lshl_add_u64 v[204:205], v[64:65], 0, s[52:53]
	global_load_dwordx4 v[192:195], v[204:205], off nt
	v_lshl_add_u64 v[204:205], v[64:65], 0, s[54:55]
	global_load_dwordx4 v[196:199], v[204:205], off nt
	v_lshl_add_u64 v[204:205], v[64:65], 0, s[56:57]
	global_load_dwordx4 v[200:203], v[204:205], off nt

.LBB0_555:
	global_load_dwordx4 v[10:13], v[220:221], off offset:16
	global_load_dwordx4 v[14:17], v[220:221], off
	global_load_dwordx4 v[6:9], v[64:65], off offset:64 nt
	s_cmp_lg_u32 s68, 4
	s_cbranch_scc1 .Lpmh_skip1
	v_lshl_add_u64 v[204:205], v[64:65], 0, s[52:53]
	global_load_dwordx4 v[192:195], v[204:205], off offset:64 nt
	v_lshl_add_u64 v[204:205], v[64:65], 0, s[54:55]
	global_load_dwordx4 v[196:199], v[204:205], off offset:64 nt
	v_lshl_add_u64 v[204:205], v[64:65], 0, s[56:57]
	global_load_dwordx4 v[200:203], v[204:205], off offset:64 nt

.LBB0_559:
	global_load_dwordx4 v[14:17], v[222:223], off offset:16
	global_load_dwordx4 v[18:21], v[222:223], off
	global_load_dwordx4 v[10:13], v[64:65], off offset:128 nt
	s_cmp_lg_u32 s68, 4
	s_cbranch_scc1 .Lpmh_skip2
	v_lshl_add_u64 v[204:205], v[64:65], 0, s[52:53]
	global_load_dwordx4 v[192:195], v[204:205], off offset:128 nt
	v_lshl_add_u64 v[204:205], v[64:65], 0, s[54:55]
	global_load_dwordx4 v[196:199], v[204:205], off offset:128 nt
	v_lshl_add_u64 v[204:205], v[64:65], 0, s[56:57]
	global_load_dwordx4 v[200:203], v[204:205], off offset:128 nt

.LBB0_563:
	global_load_dwordx4 v[22:25], v[224:225], off
	global_load_dwordx4 v[18:21], v[224:225], off offset:16
	global_load_dwordx4 v[14:17], v[64:65], off offset:192 nt
	s_cmp_lg_u32 s68, 4
	s_cbranch_scc1 .Lpmh_skip3
	v_lshl_add_u64 v[204:205], v[64:65], 0, s[52:53]
	global_load_dwordx4 v[192:195], v[204:205], off offset:192 nt
	v_lshl_add_u64 v[204:205], v[64:65], 0, s[54:55]
	global_load_dwordx4 v[196:199], v[204:205], off offset:192 nt
	v_lshl_add_u64 v[204:205], v[64:65], 0, s[56:57]
	global_load_dwordx4 v[200:203], v[204:205], off offset:192 nt
